# band items dealt evenly (96-item blocks per class) to the eight XCD queues and every workgroup serves only its own queue: no foreign-queue probing at the end of each attention phase
# speedup vs baseline: 1.0036x; 1.0036x over previous
; DI void phase_att(const Params& P, char* lds, int hb, int layer) {
;     ...
;     for (int dq = 0; dq < 8; ++dq) {
;         const int qx = (blockIdx.x + dq) & 7;
;         while (true) {
;             if (tid == 0) *slot = (int)atomicAdd(&ctr[qx], 1u);
;             __syncthreads();
;             const int qi = *slot;
;             __syncthreads();
;             if (qi >= NQ) break;
;             if (qi < 64) diff_item(P, lds, layer, qx, 63 - qi, tab_head);
;             else band_item(P, lds, layer, qx * 384 + (qi - 64));
;         }
;     }
.LBB0_195:
	s_add_i32 s26, s26, 1
	s_add_i32 s2, s2, 1
	s_branch .LBB0_270
